# mixer C: loop-top waits leave the 4 younger output stores of the previous unit in flight (vmcnt 14..6 / 13), one drain before the loop
# baseline (speedup 1.0000x reference)
; #define LAS __attribute__((address_space(3)))
; __device__ __forceinline__ void mixC_mfma(const bf16* P, const float* rpb  , bf16* MIX, LAS unsigned char* lds, int bid, int G, int tid) {
;     const int lane = tid & 63, wave = __builtin_amdgcn_readfirstlane(tid >> 6), fr = lane & 15, fq = lane >> 4;
;     LAS unsigned char* Vs = lds; LAS float* rp = (LAS float*)(lds + 576 * VROW);
;     constexpr int NU = (M / 128) * 12;
;     constexpr float L2E = 1.4426950408889634f;
;     __syncthreads();
;     for (int e = tid; e < 12 * 512; e += NTHREADS) { const int h = e >> 9, i = e & 511; rp[e] = i < 465 ? rpb[h * 465 + i] * L2E : 0.f; }
;     v4u vpre[9]; bf16x8 Qn0, Qn1, Kn[8][2];
;     const int vb_ = (G % 8 == 0) ? (bid & 7) * (G >> 3) + (bid >> 3) : bid;
;     if (vb_ < NU) c_prefetch(P, vb_, tid, wave, fr, fq, vpre, Qn0, Qn1, Kn);
;     for (int un = vb_; un < NU; un += G) {
.LBB0_351:
	v_lshlrev_b32_e32 v112, 3, v110
	v_lshlrev_b32_e32 v212, 2, v110
	v_mbcnt_lo_u32_b32 v110, -1, 0
	v_mbcnt_hi_u32_b32 v110, -1, v110
	v_and_b32_e32 v114, 64, v110
	v_xor_b32_e32 v113, 16, v110
	v_add_u32_e32 v114, 64, v114
	v_cmp_lt_i32_e32 vcc, v113, v114
	v_lshlrev_b32_e32 v1, 4, v208
	v_and_b32_e32 v1, 0x70, v1
	v_cndmask_b32_e32 v113, v110, v113, vcc
	v_lshlrev_b32_e32 v219, 2, v113
	v_xor_b32_e32 v113, 32, v110
	v_cmp_lt_i32_e32 vcc, v113, v114
	v_lshlrev_b32_e32 v114, 3, v208
	v_add_u32_e32 v111, 0, v1
	v_cndmask_b32_e32 v110, v110, v113, vcc
	v_lshlrev_b32_e32 v220, 2, v110
	v_lshrrev_b32_e32 v113, 3, v208
	v_and_b32_e32 v110, 56, v114
	v_and_b32_e32 v114, 24, v114
	s_movk_i32 s31, 0xa0
	v_add_u32_e32 v222, 0, v114
	v_mad_u32_u24 v223, v113, s31, v111
	v_add_u32_e32 v113, 0x200, v208
	v_add_u32_e32 v114, 0x600, v208
	v_add_u32_e32 v115, 0xa00, v208
	v_add_u32_e32 v116, 0xe00, v208
	s_lshr_b32 s12, s8, 8
	s_bfe_u32 s13, s8, 0x20006
	v_lshrrev_b32_e32 v113, 3, v113
	v_lshrrev_b32_e32 v114, 3, v114
	v_lshrrev_b32_e32 v115, 3, v115
	v_lshrrev_b32_e32 v116, 3, v116
	s_cmp_eq_u32 s13, 2
	v_lshl_or_b32 v1, s13, 4, v207
	v_mul_u32_u24_e32 v113, 0xa0, v113
	v_mul_u32_u24_e32 v114, 0xa0, v114
	v_mul_u32_u24_e32 v115, 0xa0, v115
	v_mul_u32_u24_e32 v116, 0xa0, v116
	s_cselect_b32 s29, 24, 32
	v_med3_u32 v209, v1, 8, 56
	v_mov_b32_e32 v211, 0
	v_bfe_u32 v221, v208, 3, 6
	v_add_u32_e32 v224, 0x14000, v223
	v_or_b32_e32 v225, v137, v212
	s_lshl_b32 s33, s68, 7
	s_lshl_b32 s34, s3, 7
	s_movk_i32 s78, 0xf800
	v_add_u32_e32 v226, v111, v113
	v_add_u32_e32 v227, v111, v114
	v_add_u32_e32 v228, v111, v115
	v_add_u32_e32 v229, v111, v116
	s_movk_i32 s79, 0x2c00
	v_lshlrev_b32_e32 v210, 1, v112
	s_mov_b64 s[22:23], 0x2000
	s_movk_i32 s88, 0x2000
	v_lshlrev_b32_e32 v214, 1, v110
	v_lshlrev_b32_e32 v216, 1, v212
	s_waitcnt vmcnt(0)
	s_branch .LBB0_353

; #define LAS __attribute__((address_space(3)))
; __device__ __forceinline__ void seq_of(int row, int& s0, int& T) { if (row < MP) { s0 = row & ~2047; T = 2048; } else { s0 = MP + ((row - MP) & ~4095); T = 4096; } }
; __device__ __forceinline__ void mixC_mfma(const bf16* P, const float* rpb  , bf16* MIX, LAS unsigned char* lds, int bid, int G, int tid) {
;     ...
;     for (int un = vb_; un < NU; un += G) {
;         const int h = un / (M / 128), blk = un - h * (M / 128), row0 = blk * 128; int s0, T; seq_of(row0, s0, T);
;         const int rows = T >> 6, rf = (row0 - s0) >> 6;
;         int R0 = rf - 4; R0 = R0 < 0 ? 0 : R0; R0 = R0 > rows - 8 ? rows - 8 : R0;
;         __syncthreads();
; #pragma unroll
;         for (int i = 0; i < 9; ++i) { const int e = tid + i * NTHREADS; *(LAS v4u*)(Vs + (e >> 3) * VROW + (e & 7) * 16) = vpre[i]; }
;         __syncthreads();
.LBB0_353:
	s_mul_hi_i32 s0, s3, 0x2aaaaaab
	s_lshr_b32 s1, s0, 31
	s_ashr_i32 s4, s0, 5
	s_add_i32 s4, s4, s1
	s_mul_i32 s0, s4, 0xffffff40
	s_mul_i32 s1, s4, 0xffffa000
	s_add_i32 s0, s3, s0
	s_add_i32 s1, s34, s1
	s_cmpk_lt_i32 s0, 0x80
	s_cselect_b32 s0, s78, 0x7ffff000
	s_cselect_b32 s5, 24, 56
	s_and_b32 s89, s0, s1
	s_mul_i32 s0, s4, 0x6000
	s_add_i32 s0, s89, s0
	s_sub_i32 s0, s34, s0
	s_ashr_i32 s90, s0, 6
	s_max_i32 s0, s90, 4
	s_add_i32 s0, s0, -4
	s_min_u32 s91, s0, s5
	s_cmp_lt_i32 s13, 1
	s_mov_b32 s35, s13
	s_waitcnt lgkmcnt(0)
	s_barrier
	s_waitcnt vmcnt(14)
	ds_write_b128 v223, v[2:5]
	s_waitcnt vmcnt(13)
	ds_write_b128 v226, v[6:9]
	s_waitcnt vmcnt(12)
	ds_write_b128 v223, v[10:13] offset:20480
	s_waitcnt vmcnt(11)
	ds_write_b128 v227, v[14:17]
	s_waitcnt vmcnt(10)
	ds_write_b128 v223, v[18:21] offset:40960
	s_waitcnt vmcnt(9)
	ds_write_b128 v228, v[22:25]
	s_waitcnt vmcnt(8)
	ds_write_b128 v223, v[26:29] offset:61440
	s_waitcnt vmcnt(7)
	ds_write_b128 v229, v[30:33]
	s_waitcnt vmcnt(6)
	ds_write_b128 v224, v[34:37]
	s_waitcnt lgkmcnt(0)
	s_barrier
	v_mov_b32_e32 v252, 0xb0000
	v_mov_b32_e32 v253, 0
	v_lshl_add_u64 v[6:7], v[100:101], 0, v[252:253]
	v_lshl_add_u64 v[10:11], v[6:7], 0, v[252:253]
	v_lshl_add_u64 v[14:15], v[10:11], 0, v[252:253]
	v_lshl_add_u64 v[18:19], v[14:15], 0, v[252:253]
	v_lshl_add_u64 v[22:23], v[18:19], 0, v[252:253]
	v_lshl_add_u64 v[26:27], v[22:23], 0, v[252:253]
	v_lshl_add_u64 v[30:31], v[26:27], 0, v[252:253]
	v_mov_b32_e32 v34, v108
	v_mov_b32_e32 v35, v109
	v_mov_b32_e32 v2, v100
	v_mov_b32_e32 v3, v101
	global_load_dwordx4 v[2:5], v[2:3], off offset:1536
	global_load_dwordx4 v[6:9], v[6:7], off offset:1536
	global_load_dwordx4 v[10:13], v[10:11], off offset:1536
	global_load_dwordx4 v[14:17], v[14:15], off offset:1536
	global_load_dwordx4 v[18:21], v[18:19], off offset:1536
	global_load_dwordx4 v[22:25], v[22:23], off offset:1536
	global_load_dwordx4 v[26:29], v[26:27], off offset:1536
	global_load_dwordx4 v[30:33], v[30:31], off offset:1536
	global_load_dwordx4 v[34:37], v[34:35], off offset:1536
	s_cbranch_scc1 .LBB0_358
	s_cmp_eq_u32 s13, 1
	s_mov_b64 s[0:1], -1
	s_cbranch_scc1 .LBB0_356
	s_mov_b64 s[0:1], 0

; __device__ __forceinline__ void mixC_mfma(const bf16* P, const float* rpb  , bf16* MIX, LAS unsigned char* lds, int bid, int G, int tid) {
;     ...
;         const int r = rf + (wave >> 2), j = wave & 3;
;         int rs = r - 4; rs = rs < 0 ? 0 : rs; rs = rs > rows - 8 ? rows - 8 : rs;
;         const int kcol0 = j == 0 ? 0 : (j == 1 ? 8 : (j == 2 ? 24 : 32));
;         const int c = 16 * j + fr; int cs = c - 8; cs = cs < 0 ? 0 : cs; cs = cs > 48 ? 48 : cs;
;         const size_t qrow = (size_t)(s0 + r * 64 + c);
;         f32x4 S[16];
;         bf16x8 Kl[8][2];
; #pragma unroll
;         for (int kt = 8; kt < 16; ++kt) { const bf16* kp = P + (size_t)(s0 + (rs + (kt >> 1)) * 64 + kcol0 + 16 * (kt & 1) + fr) * DIN + C_KC + h * 64 + fq * 8;
;             Kl[kt - 8][0] = *(const bf16x8*)kp; Kl[kt - 8][1] = *(const bf16x8*)(kp + 32); }
; #pragma unroll
;         for (int kt = 0; kt < 8; ++kt) { f32x4 z = {0.f, 0.f, 0.f, 0.f};
;             z = __builtin_amdgcn_mfma_f32_16x16x32_bf16(Kn[kt][0], Qn0, z, 0, 0, 0);
;             S[kt] = __builtin_amdgcn_mfma_f32_16x16x32_bf16(Kn[kt][1], Qn1, z, 0, 0, 0); }
.LBB0_358:
	s_add_i32 s90, s90, s12
	s_max_i32 s0, s90, 4
	s_add_i32 s0, s0, -4
	s_min_u32 s92, s0, s5
	v_mov_b32_e32 v253, s91
	v_sub_u32_e32 v253, s92, v253
	v_lshl_add_u32 v253, v253, 6, s35
	v_mul_u32_u24_e32 v253, 0xa0, v253
	v_and_b32_e32 v255, 15, v208
	v_mul_u32_u24_e32 v255, 0xa0, v255
	v_bfe_u32 v254, v208, 4, 2
	v_lshl_add_u32 v255, v254, 4, v255
	v_add_u32_e32 v255, v253, v255
	v_add_u32_e32 v254, 0xa000, v255
	ds_read_b128 v[46:49], v255
	ds_read_b128 v[50:53], v255 offset:64
	ds_read_b128 v[54:57], v255 offset:2560
	ds_read_b128 v[58:61], v255 offset:2624
	ds_read_b128 v[62:65], v255 offset:10240
	ds_read_b128 v[66:69], v255 offset:10304
	ds_read_b128 v[70:73], v255 offset:12800
	ds_read_b128 v[74:77], v255 offset:12864
	ds_read_b128 v[82:85], v255 offset:20480
	ds_read_b128 v[78:81], v255 offset:20544
	ds_read_b128 v[86:89], v255 offset:23040
	ds_read_b128 v[90:93], v255 offset:23104
	ds_read_b128 v[94:97], v255 offset:30720
	ds_read_b128 v[98:101], v255 offset:30784
	ds_read_b128 v[102:105], v255 offset:33280
	ds_read_b128 v[106:109], v255 offset:33344
	s_waitcnt lgkmcnt(0)
	v_or_b32_e32 v110, s89, v207
	s_lshl_b32 s5, s92, 6
	v_add_u32_e32 v162, s35, v110
	s_add_i32 s6, s5, 0x100
	s_lshl_b32 s80, s4, 6
	v_add_u32_e32 v110, s6, v162
	v_mov_b64_e32 v[170:171], s[74:75]
	s_ashr_i32 s81, s80, 31
	v_mad_i64_i32 v[110:111], s[0:1], v110, s79, v[170:171]
	s_lshl_b64 s[0:1], s[80:81], 1
	v_add_u32_e32 v172, 16, v162
	v_lshl_add_u64 v[110:111], v[110:111], 0, s[0:1]
	v_add_u32_e32 v118, s6, v172
	v_lshl_add_u64 v[110:111], v[110:111], 0, v[210:211]
	v_mad_i64_i32 v[118:119], s[6:7], v118, s79, v[170:171]
	s_add_i32 s8, s5, 0x140
	s_waitcnt vmcnt(13)
	v_mfma_f32_16x16x32_bf16 v[142:145], v[46:49], v[38:41], 0
	v_lshl_add_u64 v[114:115], v[110:111], 0, s[22:23]
	v_add_co_u32_e32 v110, vcc, s88, v110
	v_lshl_add_u64 v[118:119], v[118:119], 0, s[0:1]
	v_add_u32_e32 v126, s8, v162
	v_addc_co_u32_e32 v111, vcc, 0, v111, vcc
	v_lshl_add_u64 v[118:119], v[118:119], 0, v[210:211]
	v_mad_i64_i32 v[126:127], s[6:7], v126, s79, v[170:171]
	v_lshl_add_u64 v[122:123], v[118:119], 0, s[22:23]
	v_add_co_u32_e32 v118, vcc, s88, v118
	v_lshl_add_u64 v[126:127], v[126:127], 0, s[0:1]
	v_add_u32_e32 v134, s8, v172
	s_add_i32 s8, s5, 0x180
	v_addc_co_u32_e32 v119, vcc, 0, v119, vcc
	v_lshl_add_u64 v[126:127], v[126:127], 0, v[210:211]
	v_mad_i64_i32 v[134:135], s[6:7], v134, s79, v[170:171]
	s_waitcnt vmcnt(14)
	v_mfma_f32_16x16x32_bf16 v[202:205], v[50:53], v[42:45], v[142:145]
	v_lshl_add_u64 v[130:131], v[126:127], 0, s[22:23]
	v_add_co_u32_e32 v126, vcc, s88, v126
	s_nop 0
	v_add_u32_e32 v142, s8, v162
	v_lshl_add_u64 v[134:135], v[134:135], 0, s[0:1]
	v_mad_i64_i32 v[146:147], s[6:7], v142, s79, v[170:171]
	s_waitcnt vmcnt(13)
	v_mfma_f32_16x16x32_bf16 v[142:145], v[54:57], v[38:41], 0
	v_addc_co_u32_e32 v127, vcc, 0, v127, vcc
	v_lshl_add_u64 v[134:135], v[134:135], 0, v[210:211]
	v_lshl_add_u64 v[136:137], v[134:135], 0, s[22:23]
	v_add_co_u32_e32 v134, vcc, s88, v134
	v_lshl_add_u64 v[146:147], v[146:147], 0, s[0:1]
	s_nop 0
	v_addc_co_u32_e32 v135, vcc, 0, v135, vcc
	v_lshl_add_u64 v[146:147], v[146:147], 0, v[210:211]
	s_waitcnt vmcnt(12)
	v_mfma_f32_16x16x32_bf16 v[198:201], v[58:61], v[42:45], v[142:145]
	v_lshl_add_u64 v[150:151], v[146:147], 0, s[22:23]
	ds_read_b128 v[110:113], v254
	s_nop 0
	ds_read_b128 v[114:117], v254 offset:64
	v_add_co_u32_e32 v142, vcc, s88, v146
	ds_read_b128 v[118:121], v254 offset:2560
	s_nop 0
	ds_read_b128 v[122:125], v254 offset:2624
	v_addc_co_u32_e32 v143, vcc, 0, v147, vcc
	ds_read_b128 v[126:129], v254 offset:10240
	s_nop 0
	ds_read_b128 v[130:133], v254 offset:10304
	s_nop 0
	ds_read_b128 v[138:141], v254 offset:12800
	s_nop 0
	ds_read_b128 v[134:137], v254 offset:12864
	s_nop 0
	ds_read_b128 v[146:149], v254 offset:20480
	s_nop 0
	ds_read_b128 v[142:145], v254 offset:20544
	s_waitcnt vmcnt(21)
; #define LAS __attribute__((address_space(3)))
; __device__ __forceinline__ void mixC_mfma(const bf16* P, const float* rpb  , bf16* MIX, LAS unsigned char* lds, int bid, int G, int tid) {
;     ...
; #pragma unroll
;         for (int kt = 8; kt < 16; ++kt) { const bf16* kp = P + (size_t)(s0 + (rs + (kt >> 1)) * 64 + kcol0 + 16 * (kt & 1) + fr) * DIN + C_KC + h * 64 + fq * 8;
;             Kl[kt - 8][0] = *(const bf16x8*)kp; Kl[kt - 8][1] = *(const bf16x8*)(kp + 32); }
; #pragma unroll
;         for (int kt = 0; kt < 8; ++kt) { f32x4 z = {0.f, 0.f, 0.f, 0.f};
;             z = __builtin_amdgcn_mfma_f32_16x16x32_bf16(Kn[kt][0], Qn0, z, 0, 0, 0);
;             S[kt] = __builtin_amdgcn_mfma_f32_16x16x32_bf16(Kn[kt][1], Qn1, z, 0, 0, 0); }
;         const int d0 = kcol0 + 4 * fq - cs;
;         const LAS float* rpl = rp + h * 512 + (rs - r + 7) * 31 + (kcol0 + 4 * fq - c + 15);
;         float m1 = -1e30f;
; #pragma unroll
;         for (int kt = 0; kt < 8; ++kt)
; #pragma unroll
;             for (int t = 0; t < 4; ++t) {
;                 const bool ok = (unsigned)(d0 + 16 * (kt & 1) + t) < 16u;
;                 const float sv = ok ? S[kt][t] * (0.125f * L2E) + rpl[(kt >> 1) * 31 + 16 * (kt & 1) + t] : -1e30f;
;                 S[kt][t] = sv; m1 = fmaxf(m1, sv);
	v_mfma_f32_16x16x32_bf16 v[150:153], v[62:65], v[38:41], 0
	v_add_u32_e32 v154, s8, v172
	v_mad_i64_i32 v[154:155], s[6:7], v154, s79, v[170:171]
	s_waitcnt vmcnt(20)
	v_mfma_f32_16x16x32_bf16 v[194:197], v[66:69], v[42:45], v[150:153]
	s_addk_i32 s5, 0x1c0
	v_add_u32_e32 v162, s5, v162
	v_mad_i64_i32 v[162:163], s[6:7], v162, s79, v[170:171]
	s_nop 0
	v_lshl_add_u64 v[150:151], v[154:155], 0, s[0:1]
	v_lshl_add_u64 v[154:155], v[150:151], 0, v[210:211]
	s_waitcnt vmcnt(19)
	v_mfma_f32_16x16x32_bf16 v[150:153], v[70:73], v[38:41], 0
	v_lshl_add_u64 v[158:159], v[154:155], 0, s[22:23]
	v_add_co_u32_e32 v154, vcc, s88, v154
	s_waitcnt vmcnt(15)
	v_mfma_f32_16x16x32_bf16 v[166:169], v[86:89], v[38:41], 0
	v_addc_co_u32_e32 v155, vcc, 0, v155, vcc
	v_add_u32_e32 v217, s35, v212
	v_mfma_f32_16x16x32_bf16 v[190:193], v[74:77], v[42:45], v[150:153]
	ds_read_b128 v[154:157], v254 offset:23040
	s_nop 1
	ds_read_b128 v[150:153], v254 offset:23104
	v_sub_u32_e32 v215, v217, v209
	v_sub_u32_e32 v217, v217, v1
	v_mfma_f32_16x16x32_bf16 v[158:161], v[82:85], v[38:41], 0
	s_waitcnt vmcnt(16)
	v_mfma_f32_16x16x32_bf16 v[182:185], v[90:93], v[42:45], v[166:169]
	s_nop 2
	v_add_u32_e32 v166, s5, v172
	v_mfma_f32_16x16x32_bf16 v[186:189], v[78:81], v[42:45], v[158:161]
	v_mad_i64_i32 v[170:171], s[6:7], v166, s79, v[170:171]
	v_lshl_add_u64 v[170:171], v[170:171], 0, s[0:1]
	s_nop 0
	v_lshl_add_u64 v[158:159], v[162:163], 0, s[0:1]
	s_waitcnt vmcnt(15)
	v_mfma_f32_16x16x32_bf16 v[166:169], v[94:97], v[38:41], 0
	v_lshl_add_u64 v[158:159], v[158:159], 0, v[210:211]
	v_lshl_add_u64 v[160:161], v[158:159], 0, s[22:23]
	v_add_co_u32_e32 v158, vcc, s88, v158
	v_lshl_add_u64 v[170:171], v[170:171], 0, v[210:211]
	s_nop 0
	v_addc_co_u32_e32 v159, vcc, 0, v159, vcc
	s_waitcnt vmcnt(14)
	v_mfma_f32_16x16x32_bf16 v[178:181], v[98:101], v[42:45], v[166:169]
	ds_read_b128 v[162:165], v254 offset:30720
	s_nop 0
	ds_read_b128 v[158:161], v254 offset:30784
	v_add_co_u32_e32 v166, vcc, s88, v170
	v_lshl_add_u64 v[230:231], v[170:171], 0, s[22:23]
	s_nop 0
	v_addc_co_u32_e32 v167, vcc, 0, v171, vcc
	ds_read_b128 v[170:173], v254 offset:33280
	s_nop 0
	ds_read_b128 v[166:169], v254 offset:33344
	s_waitcnt vmcnt(17)
	v_mfma_f32_16x16x32_bf16 v[174:177], v[102:105], v[38:41], 0
	s_lshl_b32 s0, s4, 11
	s_sub_i32 s1, s92, s90
	s_add_i32 s0, s0, 0
	s_waitcnt vmcnt(16)
	v_mfma_f32_16x16x32_bf16 v[174:177], v[106:109], v[42:45], v[174:177]
	s_mulk_i32 s1, 0x7c
	s_add_i32 s0, s0, s1
	v_add_u32_e32 v230, 8, v215
	s_add_i32 s0, s0, 0x16800
	v_lshl_add_u32 v231, v217, 2, s0
	s_waitcnt lgkmcnt(0)
	ds_read_b32 v46, v231 offset:928
	ds_read_b32 v47, v231 offset:932
	ds_read_b32 v48, v231 offset:936
	ds_read_b32 v49, v231 offset:940
	ds_read_b32 v50, v231 offset:992
	ds_read_b32 v51, v231 offset:996
	ds_read_b32 v52, v231 offset:1000
	ds_read_b32 v53, v231 offset:1004
	ds_read_b32 v54, v231 offset:1052
	ds_read_b32 v55, v231 offset:1056
	ds_read_b32 v56, v231 offset:1060
	ds_read_b32 v57, v231 offset:1064
	ds_read_b32 v58, v231 offset:1116
	ds_read_b32 v59, v231 offset:1120
	ds_read_b32 v60, v231 offset:1124
	ds_read_b32 v61, v231 offset:1128
	v_cmp_gt_u32_e64 s[0:1], 16, v230
	v_mov_b32_e32 v217, 0xf149f2ca
	v_mov_b32_e32 v230, 0xf149f2ca
	s_and_saveexec_b64 s[4:5], s[0:1]
	s_cbranch_execz .LBB0_360
	s_waitcnt lgkmcnt(0)
	v_fmamk_f32 v230, v202, 0x3e38aa3b, v46

; #define LAS __attribute__((address_space(3)))
; __device__ __forceinline__ void mixC_mfma(const bf16* P, const float* rpb  , bf16* MIX, LAS unsigned char* lds, int bid, int G, int tid) {
;     const int lane = tid & 63, wave = __builtin_amdgcn_readfirstlane(tid >> 6), fr = lane & 15, fq = lane >> 4;
;     LAS unsigned char* Vs = lds; LAS float* rp = (LAS float*)(lds + 576 * VROW);
;     constexpr int NU = (M / 128) * 12;
;     constexpr float L2E = 1.4426950408889634f;
;     __syncthreads();
;     for (int e = tid; e < 12 * 512; e += NTHREADS) { const int h = e >> 9, i = e & 511; rp[e] = i < 465 ? rpb[h * 465 + i] * L2E : 0.f; }
;     v4u vpre[9]; bf16x8 Qn0, Qn1, Kn[8][2];
;     const int vb_ = (G % 8 == 0) ? (bid & 7) * (G >> 3) + (bid >> 3) : bid;
;     if (vb_ < NU) c_prefetch(P, vb_, tid, wave, fr, fq, vpre, Qn0, Qn1, Kn);
;     for (int un = vb_; un < NU; un += G) {
.LBB0_1376:
	v_lshlrev_b32_e32 v112, 3, v110
	v_lshlrev_b32_e32 v212, 2, v110
	v_mbcnt_lo_u32_b32 v110, -1, 0
	v_mbcnt_hi_u32_b32 v110, -1, v110
	v_and_b32_e32 v114, 64, v110
	v_xor_b32_e32 v113, 16, v110
	v_add_u32_e32 v114, 64, v114
	v_cmp_lt_i32_e32 vcc, v113, v114
	v_lshlrev_b32_e32 v1, 4, v208
	v_and_b32_e32 v1, 0x70, v1
	v_cndmask_b32_e32 v113, v110, v113, vcc
	v_lshlrev_b32_e32 v219, 2, v113
	v_xor_b32_e32 v113, 32, v110
	v_cmp_lt_i32_e32 vcc, v113, v114
	v_lshlrev_b32_e32 v114, 3, v208
	v_add_u32_e32 v111, 0, v1
	v_cndmask_b32_e32 v110, v110, v113, vcc
	v_lshlrev_b32_e32 v220, 2, v110
	v_lshrrev_b32_e32 v113, 3, v208
	v_and_b32_e32 v110, 56, v114
	v_and_b32_e32 v114, 24, v114
	s_movk_i32 s53, 0xa0
	v_add_u32_e32 v222, 0, v114
	v_mad_u32_u24 v223, v113, s53, v111
	v_add_u32_e32 v113, 0x200, v208
	v_add_u32_e32 v114, 0x600, v208
	v_add_u32_e32 v115, 0xa00, v208
	v_add_u32_e32 v116, 0xe00, v208
	s_lshr_b32 s13, s8, 8
	s_bfe_u32 s33, s8, 0x20006
	v_lshrrev_b32_e32 v113, 3, v113
	v_lshrrev_b32_e32 v114, 3, v114
	v_lshrrev_b32_e32 v115, 3, v115
	v_lshrrev_b32_e32 v116, 3, v116
	s_cmp_eq_u32 s33, 2
	v_lshl_or_b32 v1, s33, 4, v213
	v_mul_u32_u24_e32 v113, 0xa0, v113
	v_mul_u32_u24_e32 v114, 0xa0, v114
	v_mul_u32_u24_e32 v115, 0xa0, v115
	v_mul_u32_u24_e32 v116, 0xa0, v116
	s_cselect_b32 s52, 24, 32
	v_med3_u32 v209, v1, 8, 56
	v_mov_b32_e32 v211, 0
	v_bfe_u32 v221, v208, 3, 6
	v_add_u32_e32 v224, 0x14000, v223
	v_or_b32_e32 v225, v137, v212
	s_lshl_b32 s56, s68, 7
	s_lshl_b32 s57, s12, 7
	s_movk_i32 s78, 0xf800
	v_add_u32_e32 v226, v111, v113
	v_add_u32_e32 v227, v111, v114
	v_add_u32_e32 v228, v111, v115
	v_add_u32_e32 v229, v111, v116
	s_movk_i32 s79, 0x2c00
	v_lshlrev_b32_e32 v210, 1, v112
	s_mov_b64 s[20:21], 0x2000
	s_movk_i32 s80, 0x2000
	v_lshlrev_b32_e32 v214, 1, v110
	s_mov_b64 s[22:23], 0x1a00
	s_movk_i32 s81, 0xc00
	v_lshlrev_b32_e32 v216, 1, v212
	s_waitcnt vmcnt(0)
	s_branch .LBB0_1378

; #define LAS __attribute__((address_space(3)))
; __device__ __forceinline__ void seq_of(int row, int& s0, int& T) { if (row < MP) { s0 = row & ~2047; T = 2048; } else { s0 = MP + ((row - MP) & ~4095); T = 4096; } }
; __device__ __forceinline__ void mixC_mfma(const bf16* P, const float* rpb  , bf16* MIX, LAS unsigned char* lds, int bid, int G, int tid) {
;     ...
;     for (int un = vb_; un < NU; un += G) {
;         const int h = un / (M / 128), blk = un - h * (M / 128), row0 = blk * 128; int s0, T; seq_of(row0, s0, T);
;         const int rows = T >> 6, rf = (row0 - s0) >> 6;
;         int R0 = rf - 4; R0 = R0 < 0 ? 0 : R0; R0 = R0 > rows - 8 ? rows - 8 : R0;
;         __syncthreads();
; #pragma unroll
;         for (int i = 0; i < 9; ++i) { const int e = tid + i * NTHREADS; *(LAS v4u*)(Vs + (e >> 3) * VROW + (e & 7) * 16) = vpre[i]; }
;         __syncthreads();
.LBB0_1378:
	s_mul_hi_i32 s0, s12, 0x2aaaaaab
	s_lshr_b32 s1, s0, 31
	s_ashr_i32 s4, s0, 5
	s_add_i32 s4, s4, s1
	s_mul_i32 s0, s4, 0xffffff40
	s_mul_i32 s1, s4, 0xffffa000
	s_add_i32 s0, s12, s0
	s_add_i32 s1, s57, s1
	s_cmpk_lt_i32 s0, 0x80
	s_cselect_b32 s0, s78, 0x7ffff000
	s_cselect_b32 s5, 24, 56
	s_and_b32 s82, s0, s1
	s_mul_i32 s0, s4, 0x6000
	s_add_i32 s0, s82, s0
	s_sub_i32 s0, s57, s0
	s_ashr_i32 s83, s0, 6
	s_max_i32 s0, s83, 4
	s_add_i32 s0, s0, -4
	s_min_u32 s84, s0, s5
	s_cmp_lt_i32 s33, 1
	s_mov_b32 s85, s33
	s_waitcnt lgkmcnt(0)
	s_barrier
	s_waitcnt vmcnt(14)
	ds_write_b128 v223, v[2:5]
	s_waitcnt vmcnt(13)
	ds_write_b128 v226, v[6:9]
	s_waitcnt vmcnt(12)
	ds_write_b128 v223, v[10:13] offset:20480
	s_waitcnt vmcnt(11)
	ds_write_b128 v227, v[14:17]
	s_waitcnt vmcnt(10)
	ds_write_b128 v223, v[18:21] offset:40960
	s_waitcnt vmcnt(9)
	ds_write_b128 v228, v[22:25]
	s_waitcnt vmcnt(8)
	ds_write_b128 v223, v[26:29] offset:61440
	s_waitcnt vmcnt(7)
	ds_write_b128 v229, v[30:33]
	s_waitcnt vmcnt(6)
	ds_write_b128 v224, v[34:37]
	s_waitcnt lgkmcnt(0)
	s_barrier
	v_mov_b32_e32 v252, 0xb0000
	v_mov_b32_e32 v253, 0
	v_lshl_add_u64 v[6:7], v[100:101], 0, v[252:253]
	v_lshl_add_u64 v[10:11], v[6:7], 0, v[252:253]
	v_lshl_add_u64 v[14:15], v[10:11], 0, v[252:253]
	v_lshl_add_u64 v[18:19], v[14:15], 0, v[252:253]
	v_lshl_add_u64 v[22:23], v[18:19], 0, v[252:253]
	v_lshl_add_u64 v[26:27], v[22:23], 0, v[252:253]
	v_lshl_add_u64 v[30:31], v[26:27], 0, v[252:253]
	v_mov_b32_e32 v34, v108
	v_mov_b32_e32 v35, v109
	v_mov_b32_e32 v2, v100
	v_mov_b32_e32 v3, v101
	global_load_dwordx4 v[2:5], v[2:3], off offset:1536
	global_load_dwordx4 v[6:9], v[6:7], off offset:1536
	global_load_dwordx4 v[10:13], v[10:11], off offset:1536
	global_load_dwordx4 v[14:17], v[14:15], off offset:1536
	global_load_dwordx4 v[18:21], v[18:19], off offset:1536
	global_load_dwordx4 v[22:25], v[22:23], off offset:1536
	global_load_dwordx4 v[26:29], v[26:27], off offset:1536
	global_load_dwordx4 v[30:33], v[30:31], off offset:1536
	global_load_dwordx4 v[34:37], v[34:35], off offset:1536
	s_cbranch_scc1 .LBB0_1383
	s_cmp_eq_u32 s33, 1
	s_mov_b64 s[0:1], -1
	s_cbranch_scc1 .LBB0_1381
	s_mov_b64 s[0:1], 0

; __device__ __forceinline__ void mixC_mfma(const bf16* P, const float* rpb  , bf16* MIX, LAS unsigned char* lds, int bid, int G, int tid) {
;     ...
;         const int r = rf + (wave >> 2), j = wave & 3;
;         int rs = r - 4; rs = rs < 0 ? 0 : rs; rs = rs > rows - 8 ? rows - 8 : rs;
;         const int kcol0 = j == 0 ? 0 : (j == 1 ? 8 : (j == 2 ? 24 : 32));
;         const int c = 16 * j + fr; int cs = c - 8; cs = cs < 0 ? 0 : cs; cs = cs > 48 ? 48 : cs;
;         const size_t qrow = (size_t)(s0 + r * 64 + c);
;         f32x4 S[16];
;         bf16x8 Kl[8][2];
; #pragma unroll
;         for (int kt = 8; kt < 16; ++kt) { const bf16* kp = P + (size_t)(s0 + (rs + (kt >> 1)) * 64 + kcol0 + 16 * (kt & 1) + fr) * DIN + C_KC + h * 64 + fq * 8;
;             Kl[kt - 8][0] = *(const bf16x8*)kp; Kl[kt - 8][1] = *(const bf16x8*)(kp + 32); }
; #pragma unroll
;         for (int kt = 0; kt < 8; ++kt) { f32x4 z = {0.f, 0.f, 0.f, 0.f};
;             z = __builtin_amdgcn_mfma_f32_16x16x32_bf16(Kn[kt][0], Qn0, z, 0, 0, 0);
;             S[kt] = __builtin_amdgcn_mfma_f32_16x16x32_bf16(Kn[kt][1], Qn1, z, 0, 0, 0); }
.LBB0_1383:
	s_add_i32 s83, s83, s13
	s_max_i32 s0, s83, 4
	s_add_i32 s0, s0, -4
	s_min_u32 s86, s0, s5
	v_mov_b32_e32 v253, s84
	v_sub_u32_e32 v253, s86, v253
	v_lshl_add_u32 v253, v253, 6, s85
	v_mul_u32_u24_e32 v253, 0xa0, v253
	v_and_b32_e32 v255, 15, v208
	v_mul_u32_u24_e32 v255, 0xa0, v255
	v_bfe_u32 v254, v208, 4, 2
	v_lshl_add_u32 v255, v254, 4, v255
	v_add_u32_e32 v255, v253, v255
	v_add_u32_e32 v254, 0xa000, v255
	ds_read_b128 v[46:49], v255
	ds_read_b128 v[50:53], v255 offset:64
	ds_read_b128 v[54:57], v255 offset:2560
	ds_read_b128 v[58:61], v255 offset:2624
	ds_read_b128 v[62:65], v255 offset:10240
	ds_read_b128 v[66:69], v255 offset:10304
	ds_read_b128 v[70:73], v255 offset:12800
	ds_read_b128 v[74:77], v255 offset:12864
	ds_read_b128 v[82:85], v255 offset:20480
	ds_read_b128 v[78:81], v255 offset:20544
	ds_read_b128 v[86:89], v255 offset:23040
	ds_read_b128 v[90:93], v255 offset:23104
	ds_read_b128 v[94:97], v255 offset:30720
	ds_read_b128 v[98:101], v255 offset:30784
	ds_read_b128 v[102:105], v255 offset:33280
	ds_read_b128 v[106:109], v255 offset:33344
	s_waitcnt lgkmcnt(0)
	v_or_b32_e32 v110, s82, v213
	s_lshl_b32 s5, s86, 6
	v_add_u32_e32 v162, s85, v110
	s_add_i32 s6, s5, 0x100
	s_lshl_b32 s24, s4, 6
	v_add_u32_e32 v110, s6, v162
	v_mov_b64_e32 v[170:171], s[74:75]
	s_ashr_i32 s25, s24, 31
	v_mad_i64_i32 v[110:111], s[0:1], v110, s79, v[170:171]
	s_lshl_b64 s[0:1], s[24:25], 1
	v_add_u32_e32 v172, 16, v162
	v_lshl_add_u64 v[110:111], v[110:111], 0, s[0:1]
	v_add_u32_e32 v118, s6, v172
	v_lshl_add_u64 v[110:111], v[110:111], 0, v[210:211]
	v_mad_i64_i32 v[118:119], s[6:7], v118, s79, v[170:171]
	s_add_i32 s8, s5, 0x140
	s_waitcnt vmcnt(13)
	v_mfma_f32_16x16x32_bf16 v[142:145], v[46:49], v[38:41], 0
	v_lshl_add_u64 v[114:115], v[110:111], 0, s[20:21]
	v_add_co_u32_e32 v110, vcc, s80, v110
	v_lshl_add_u64 v[118:119], v[118:119], 0, s[0:1]
	v_add_u32_e32 v126, s8, v162
	v_addc_co_u32_e32 v111, vcc, 0, v111, vcc
	v_lshl_add_u64 v[118:119], v[118:119], 0, v[210:211]
	v_mad_i64_i32 v[126:127], s[6:7], v126, s79, v[170:171]
	v_lshl_add_u64 v[122:123], v[118:119], 0, s[20:21]
	v_add_co_u32_e32 v118, vcc, s80, v118
	v_lshl_add_u64 v[126:127], v[126:127], 0, s[0:1]
	v_add_u32_e32 v134, s8, v172
	s_add_i32 s8, s5, 0x180
	v_addc_co_u32_e32 v119, vcc, 0, v119, vcc
	v_lshl_add_u64 v[126:127], v[126:127], 0, v[210:211]
	v_mad_i64_i32 v[134:135], s[6:7], v134, s79, v[170:171]
	s_waitcnt vmcnt(14)
	v_mfma_f32_16x16x32_bf16 v[202:205], v[50:53], v[42:45], v[142:145]
	v_lshl_add_u64 v[130:131], v[126:127], 0, s[20:21]
	v_add_co_u32_e32 v126, vcc, s80, v126
	s_nop 0
	v_add_u32_e32 v142, s8, v162
	v_lshl_add_u64 v[134:135], v[134:135], 0, s[0:1]
	v_mad_i64_i32 v[146:147], s[6:7], v142, s79, v[170:171]
	s_waitcnt vmcnt(13)
	v_mfma_f32_16x16x32_bf16 v[142:145], v[54:57], v[38:41], 0
	v_addc_co_u32_e32 v127, vcc, 0, v127, vcc
	v_lshl_add_u64 v[134:135], v[134:135], 0, v[210:211]
	v_lshl_add_u64 v[136:137], v[134:135], 0, s[20:21]
	v_add_co_u32_e32 v134, vcc, s80, v134
	v_lshl_add_u64 v[146:147], v[146:147], 0, s[0:1]
	s_nop 0
	v_addc_co_u32_e32 v135, vcc, 0, v135, vcc
	v_lshl_add_u64 v[146:147], v[146:147], 0, v[210:211]
	s_waitcnt vmcnt(12)
	v_mfma_f32_16x16x32_bf16 v[198:201], v[58:61], v[42:45], v[142:145]
	v_lshl_add_u64 v[150:151], v[146:147], 0, s[20:21]
	ds_read_b128 v[110:113], v254
	s_nop 0
	ds_read_b128 v[114:117], v254 offset:64
	v_add_co_u32_e32 v142, vcc, s80, v146
	ds_read_b128 v[118:121], v254 offset:2560
	s_nop 0
	ds_read_b128 v[122:125], v254 offset:2624
	v_addc_co_u32_e32 v143, vcc, 0, v147, vcc
	ds_read_b128 v[126:129], v254 offset:10240
	s_nop 0
	ds_read_b128 v[130:133], v254 offset:10304
	s_nop 0
	ds_read_b128 v[138:141], v254 offset:12800
	s_nop 0
	ds_read_b128 v[134:137], v254 offset:12864
	s_nop 0
	ds_read_b128 v[146:149], v254 offset:20480
	s_nop 0
	ds_read_b128 v[142:145], v254 offset:20544
	s_waitcnt vmcnt(21)
; #define LAS __attribute__((address_space(3)))
; __device__ __forceinline__ void mixC_mfma(const bf16* P, const float* rpb  , bf16* MIX, LAS unsigned char* lds, int bid, int G, int tid) {
;     ...
;         for (int kt = 0; kt < 8; ++kt) { f32x4 z = {0.f, 0.f, 0.f, 0.f};
;             z = __builtin_amdgcn_mfma_f32_16x16x32_bf16(Kn[kt][0], Qn0, z, 0, 0, 0);
;             S[kt] = __builtin_amdgcn_mfma_f32_16x16x32_bf16(Kn[kt][1], Qn1, z, 0, 0, 0); }
;         const int d0 = kcol0 + 4 * fq - cs;
;         const LAS float* rpl = rp + h * 512 + (rs - r + 7) * 31 + (kcol0 + 4 * fq - c + 15);
;         float m1 = -1e30f;
; #pragma unroll
;         for (int kt = 0; kt < 8; ++kt)
; #pragma unroll
;             for (int t = 0; t < 4; ++t) {
;                 const bool ok = (unsigned)(d0 + 16 * (kt & 1) + t) < 16u;
;                 const float sv = ok ? S[kt][t] * (0.125f * L2E) + rpl[(kt >> 1) * 31 + 16 * (kt & 1) + t] : -1e30f;
;                 S[kt][t] = sv; m1 = fmaxf(m1, sv);
	v_mfma_f32_16x16x32_bf16 v[150:153], v[62:65], v[38:41], 0
	v_add_u32_e32 v154, s8, v172
	v_mad_i64_i32 v[154:155], s[6:7], v154, s79, v[170:171]
	s_waitcnt vmcnt(20)
	v_mfma_f32_16x16x32_bf16 v[194:197], v[66:69], v[42:45], v[150:153]
	s_addk_i32 s5, 0x1c0
	v_add_u32_e32 v162, s5, v162
	v_mad_i64_i32 v[162:163], s[6:7], v162, s79, v[170:171]
	s_nop 0
	v_lshl_add_u64 v[150:151], v[154:155], 0, s[0:1]
	v_lshl_add_u64 v[154:155], v[150:151], 0, v[210:211]
	s_waitcnt vmcnt(19)
	v_mfma_f32_16x16x32_bf16 v[150:153], v[70:73], v[38:41], 0
	v_lshl_add_u64 v[158:159], v[154:155], 0, s[20:21]
	v_add_co_u32_e32 v154, vcc, s80, v154
	s_waitcnt vmcnt(15)
	v_mfma_f32_16x16x32_bf16 v[166:169], v[86:89], v[38:41], 0
	v_addc_co_u32_e32 v155, vcc, 0, v155, vcc
	v_add_u32_e32 v217, s85, v212
	v_mfma_f32_16x16x32_bf16 v[190:193], v[74:77], v[42:45], v[150:153]
	ds_read_b128 v[154:157], v254 offset:23040
	s_nop 1
	ds_read_b128 v[150:153], v254 offset:23104
	v_sub_u32_e32 v215, v217, v209
	v_sub_u32_e32 v217, v217, v1
	v_mfma_f32_16x16x32_bf16 v[158:161], v[82:85], v[38:41], 0
	s_waitcnt vmcnt(16)
	v_mfma_f32_16x16x32_bf16 v[182:185], v[90:93], v[42:45], v[166:169]
	s_nop 2
	v_add_u32_e32 v166, s5, v172
	v_mfma_f32_16x16x32_bf16 v[186:189], v[78:81], v[42:45], v[158:161]
	v_mad_i64_i32 v[170:171], s[6:7], v166, s79, v[170:171]
	v_lshl_add_u64 v[170:171], v[170:171], 0, s[0:1]
	s_nop 0
	v_lshl_add_u64 v[158:159], v[162:163], 0, s[0:1]
	s_waitcnt vmcnt(15)
	v_mfma_f32_16x16x32_bf16 v[166:169], v[94:97], v[38:41], 0
	v_lshl_add_u64 v[158:159], v[158:159], 0, v[210:211]
	v_lshl_add_u64 v[160:161], v[158:159], 0, s[20:21]
	v_add_co_u32_e32 v158, vcc, s80, v158
	v_lshl_add_u64 v[170:171], v[170:171], 0, v[210:211]
	s_nop 0
	v_addc_co_u32_e32 v159, vcc, 0, v159, vcc
	s_waitcnt vmcnt(14)
	v_mfma_f32_16x16x32_bf16 v[178:181], v[98:101], v[42:45], v[166:169]
	ds_read_b128 v[162:165], v254 offset:30720
	s_nop 0
	ds_read_b128 v[158:161], v254 offset:30784
	v_add_co_u32_e32 v166, vcc, s80, v170
	v_lshl_add_u64 v[230:231], v[170:171], 0, s[20:21]
	s_nop 0
	v_addc_co_u32_e32 v167, vcc, 0, v171, vcc
	ds_read_b128 v[170:173], v254 offset:33280
	s_nop 0
	ds_read_b128 v[166:169], v254 offset:33344
	s_waitcnt vmcnt(17)
	v_mfma_f32_16x16x32_bf16 v[174:177], v[102:105], v[38:41], 0
	s_lshl_b32 s0, s4, 11
	s_sub_i32 s1, s86, s83
	s_add_i32 s0, s0, 0
	s_waitcnt vmcnt(16)
	v_mfma_f32_16x16x32_bf16 v[174:177], v[106:109], v[42:45], v[174:177]
	s_mulk_i32 s1, 0x7c
	s_add_i32 s0, s0, s1
	v_add_u32_e32 v230, 8, v215
	s_add_i32 s0, s0, 0x16800
	v_lshl_add_u32 v231, v217, 2, s0
	s_waitcnt lgkmcnt(0)
	ds_read_b32 v46, v231 offset:928
	ds_read_b32 v47, v231 offset:932
	ds_read_b32 v48, v231 offset:936
	ds_read_b32 v49, v231 offset:940
	ds_read_b32 v50, v231 offset:992
	ds_read_b32 v51, v231 offset:996
	ds_read_b32 v52, v231 offset:1000
	ds_read_b32 v53, v231 offset:1004
	ds_read_b32 v54, v231 offset:1052
	ds_read_b32 v55, v231 offset:1056
	ds_read_b32 v56, v231 offset:1060
	ds_read_b32 v57, v231 offset:1064
	ds_read_b32 v58, v231 offset:1116
	ds_read_b32 v59, v231 offset:1120
	ds_read_b32 v60, v231 offset:1124
	ds_read_b32 v61, v231 offset:1128
	v_cmp_gt_u32_e64 s[0:1], 16, v230
	v_mov_b32_e32 v217, 0xf149f2ca
	v_mov_b32_e32 v230, 0xf149f2ca
	s_and_saveexec_b64 s[4:5], s[0:1]
	s_cbranch_execz .LBB0_1385
	s_waitcnt lgkmcnt(0)
	v_fmamk_f32 v230, v202, 0x3e38aa3b, v46
